# partial-count attempt threshold lowered from 2048 to 1024 known survivors
# speedup vs baseline: 1.0107x; 1.0050x over previous
; #define PAIR_XCHG(SLOT, TAG, MINE, OTHER) do { const unsigned tg_ = (seq << 8) | (unsigned)(TAG); if (lane == 0) xw[w * 4 + (SLOT)] = ((MINE) << 16) | tg_; \
;             unsigned v_; do { v_ = xw[(w ^ 1) * 4 + (SLOT)]; } while ((v_ & 0xffffu) != tg_); OTHER = v_ >> 16; } while (0)
; __device__ __forceinline__ void attn_item(const Ptrs& P, unsigned char* lds, int b, int tq0, int tid) {
;     ...
;             const unsigned cand = th | (1u << bit); unsigned cnt = 0, oth;
; #pragma unroll
;             for (int k = 0; k < 4; ++k) if (16 * k < nact) {
; #pragma unroll
;                 for (int r = 16 * k; r < 16 * k + 16; ++r) cnt += (unsigned)__popcll(__ballot(k2[r] >= cand)); }
;             PAIR_XCHG(bit & 1, 1 + bit, cnt, oth);
;             cnt += oth;
;             if (cnt >= 256u) th = cand;
;             if (cnt == 256u) break;
.Lbis_loop:
	s_lshl_b32 s12, 1, s75
	s_or_b32 s12, s85, s12
	s_lshr_b32 s13, s12, 16
	s_cmp_gt_u32 s13, s84
	s_cbranch_scc1 .Lbis_next
	v_mov_b32_e32 v24, s12
	v_mov_b32_e32 v25, 0
	v_add_u32_e32 v26, -1, v24
	s_mov_b32 s90, 0
	s_cmp_lt_u32 s97, 0x400
	s_cbranch_scc1 .Lbis_full
	s_cmp_lt_u32 s93, 64
	s_cbranch_scc1 .Lbis_full
	v_med3_u32 v38, v6, v26, v24
	v_med3_u32 v39, v95, v26, v24
	v_add3_u32 v25, v25, v38, v39
	v_med3_u32 v40, v94, v26, v24
	v_med3_u32 v41, v93, v26, v24
	v_add3_u32 v25, v25, v40, v41
	v_med3_u32 v42, v92, v26, v24
	v_med3_u32 v43, v91, v26, v24
	v_add3_u32 v25, v25, v42, v43
	v_med3_u32 v44, v90, v26, v24
	v_med3_u32 v45, v89, v26, v24
	v_add3_u32 v25, v25, v44, v45
	v_med3_u32 v38, v88, v26, v24
	v_med3_u32 v39, v87, v26, v24
	v_add3_u32 v25, v25, v38, v39
	v_med3_u32 v40, v86, v26, v24
	v_med3_u32 v41, v85, v26, v24
	v_add3_u32 v25, v25, v40, v41
	v_med3_u32 v42, v84, v26, v24
	v_med3_u32 v43, v83, v26, v24
	v_add3_u32 v25, v25, v42, v43
	v_med3_u32 v44, v82, v26, v24
	v_med3_u32 v45, v81, v26, v24
	v_add3_u32 v25, v25, v44, v45
	s_mov_b32 s90, 16
	s_sub_u32 s91, s12, 1
	s_mul_i32 s91, s91, s90
	v_subrev_u32_e32 v25, s91, v25
	s_add_i32 s13, s75, 1
	s_or_b32 s13, s86, s13
	v_add_u32_dpp v25, v25, v25 row_ror:1 row_mask:0xf bank_mask:0xf
	s_nop 1
	v_add_u32_dpp v25, v25, v25 row_ror:2 row_mask:0xf bank_mask:0xf
	s_nop 1
	v_add_u32_dpp v25, v25, v25 row_ror:4 row_mask:0xf bank_mask:0xf
	s_nop 1
	v_add_u32_dpp v25, v25, v25 row_ror:8 row_mask:0xf bank_mask:0xf
	v_mov_b32_e32 v36, s87
	v_mov_b32_e32 v37, s88
	v_readlane_b32 s78, v25, 0
	v_readlane_b32 s79, v25, 16
	v_readlane_b32 s90, v25, 32
	v_readlane_b32 s91, v25, 48
	s_mov_b64 s[44:45], exec
	s_nop 2
	s_add_i32 s78, s78, s79
	s_add_i32 s90, s90, s91
	s_add_i32 s78, s78, s90
	s_lshl_b32 s20, s78, 16
	s_or_b32 s20, s20, s13
	v_mov_b32_e32 v27, s20
	s_mov_b64 exec, s[4:5]
	ds_write_b32 v36, v27
	s_mov_b64 exec, s[44:45]
